# diff-attention loops: hazard s_nops replaced by reordering (ds_read between v_exp and its consumer; v_cmp/v_mov moved into permlane wait states)
# speedup vs baseline: 1.0050x; 1.0010x over previous
.LBB0_563:
	s_add_i32 s13, s12, -1
	s_min_u32 s34, s13, s4
	s_lshl_b64 s[30:31], s[34:35], 13
	v_lshl_add_u64 v[2:3], v[224:225], 0, s[30:31]
	global_load_dwordx4 v[196:199], v[2:3], off
	v_add_co_u32_e32 v2, vcc, s1, v218
	s_nop 1
	v_addc_co_u32_e32 v3, vcc, -1, v219, vcc
	global_load_dwordx4 v[200:203], v[2:3], off offset:-4096
	global_load_dwordx4 v[204:207], v[2:3], off
	ds_read_b128 v[2:5], v243 offset:4608
	ds_read_b128 v[6:9], v243
	ds_read_b128 v[12:15], v242 offset:59392
	s_waitcnt lgkmcnt(0)
	v_mfma_f32_32x32x16_bf16 v[160:175], v[6:9], v[12:15], v[96:111]
	ds_read_b128 v[112:115], v243 offset:32
	ds_read_b128 v[116:119], v242 offset:60416
	v_exp_f32_e32 v0, v128
	v_exp_f32_e32 v6, v129
	v_add_f32_e32 v7, 0, v0
	v_add_f32_e32 v11, v6, v7
	v_cvt_pk_bf16_f32 v10, v0, v6
	v_mfma_f32_32x32x16_bf16 v[144:159], v[2:5], v[12:15], v[96:111]
	ds_read_b128 v[6:9], v243 offset:4640
	v_exp_f32_e32 v0, v130
	v_exp_f32_e32 v120, v131
	v_add_f32_e32 v121, v0, v11
	v_cvt_pk_bf16_f32 v11, v0, v120
	v_add_f32_e32 v0, v120, v121
	s_waitcnt lgkmcnt(1)
	v_mfma_f32_32x32x16_bf16 v[160:175], v[112:115], v[116:119], v[160:175]
	ds_read_b128 v[2:5], v243 offset:64
	ds_read_b128 v[120:123], v242 offset:61440
	v_exp_f32_e32 v12, v132
	v_exp_f32_e32 v13, v133
	v_add_f32_e32 v0, v12, v0
	v_add_f32_e32 v0, v13, v0
	v_cvt_pk_bf16_f32 v12, v12, v13
	s_waitcnt lgkmcnt(2)
	v_mfma_f32_32x32x16_bf16 v[144:159], v[6:9], v[116:119], v[144:159]
	ds_read_b128 v[112:115], v243 offset:4672
	v_exp_f32_e32 v6, v134
	v_exp_f32_e32 v7, v135
	v_add_f32_e32 v0, v6, v0
	v_add_f32_e32 v0, v7, v0
	v_cvt_pk_bf16_f32 v13, v6, v7
	s_waitcnt lgkmcnt(1)
	v_mfma_f32_32x32x16_bf16 v[160:175], v[2:5], v[120:123], v[160:175]
	ds_read_b128 v[116:119], v243 offset:96
	ds_read_b128 v[124:127], v242 offset:62464
	v_exp_f32_e32 v2, v136
	v_exp_f32_e32 v3, v137
	v_add_f32_e32 v0, v2, v0
	v_add_f32_e32 v0, v3, v0
	v_cvt_pk_bf16_f32 v6, v2, v3
	s_waitcnt lgkmcnt(2)
	v_mfma_f32_32x32x16_bf16 v[144:159], v[112:115], v[120:123], v[144:159]
	ds_read_b128 v[2:5], v243 offset:4704
	v_exp_f32_e32 v7, v138
	v_exp_f32_e32 v8, v139
	v_add_f32_e32 v0, v7, v0
	v_add_f32_e32 v0, v8, v0
	v_cvt_pk_bf16_f32 v7, v7, v8
	s_waitcnt lgkmcnt(1)
	v_mfma_f32_32x32x16_bf16 v[160:175], v[116:119], v[124:127], v[160:175]
	ds_read_b64_tr_b16 v[112:113], v244 offset:18432
	ds_read_b64_tr_b16 v[114:115], v244 offset:20992
	v_exp_f32_e32 v8, v140
	v_exp_f32_e32 v9, v141
	v_add_f32_e32 v0, v8, v0
	v_add_f32_e32 v0, v9, v0
	v_cvt_pk_bf16_f32 v8, v8, v9
	s_waitcnt lgkmcnt(2)
	v_mfma_f32_32x32x16_bf16 v[144:159], v[2:5], v[124:127], v[144:159]
	ds_read_b64_tr_b16 v[116:117], v244 offset:18496
	ds_read_b64_tr_b16 v[118:119], v244 offset:21056
	v_exp_f32_e32 v9, v142
	v_exp_f32_e32 v14, v143
	v_add_f32_e32 v0, v9, v0
	v_add_f32_e32 v0, v14, v0
	v_cvt_pk_bf16_f32 v9, v9, v14
	s_waitcnt lgkmcnt(2)
	v_mfma_f32_32x32x16_bf16 v[64:79], v[112:115], v[188:191], v[64:79]
	ds_read_b64_tr_b16 v[120:121], v244 offset:18560
	ds_read_b64_tr_b16 v[122:123], v244 offset:21120
	v_exp_f32_e32 v2, v80
	v_max3_f32 v3, v160, s33, v144
	v_add_f32_e32 v0, v2, v0
	s_waitcnt lgkmcnt(2)
	v_mfma_f32_32x32x16_bf16 v[48:63], v[116:119], v[188:191], v[48:63]
	ds_read_b64_tr_b16 v[112:113], v244 offset:18624
	ds_read_b64_tr_b16 v[114:115], v244 offset:21184
	v_exp_f32_e32 v4, v81
	v_max3_f32 v3, v3, v161, v145
	v_add_f32_e32 v0, v4, v0
	v_cvt_pk_bf16_f32 v2, v2, v4
	s_waitcnt lgkmcnt(2)
	v_mfma_f32_32x32x16_bf16 v[32:47], v[120:123], v[188:191], v[32:47]
	ds_read_b64_tr_b16 v[116:117], v244 offset:23552
	ds_read_b64_tr_b16 v[118:119], v244 offset:26112
	v_exp_f32_e32 v4, v82
	v_max3_f32 v5, v3, v162, v146
	v_add_f32_e32 v0, v4, v0
	s_waitcnt lgkmcnt(2)
	v_mfma_f32_32x32x16_bf16 v[16:31], v[112:115], v[188:191], v[16:31]
	ds_read_b64_tr_b16 v[120:121], v244 offset:23616
	v_exp_f32_e32 v3, v83
	ds_read_b64_tr_b16 v[122:123], v244 offset:26176
	v_add_f32_e32 v0, v3, v0
	v_cvt_pk_bf16_f32 v3, v4, v3
	v_max3_f32 v4, v5, v163, v147
	s_waitcnt lgkmcnt(2)
	v_mfma_f32_32x32x16_bf16 v[64:79], v[116:119], v[184:187], v[64:79]
	ds_read_b64_tr_b16 v[80:81], v244 offset:23680
	ds_read_b64_tr_b16 v[82:83], v244 offset:26240
	v_exp_f32_e32 v5, v84
	v_max3_f32 v14, v4, v164, v148
	v_add_f32_e32 v0, v5, v0
	s_waitcnt lgkmcnt(2)
	v_mfma_f32_32x32x16_bf16 v[48:63], v[120:123], v[184:187], v[48:63]
	ds_read_b64_tr_b16 v[112:113], v244 offset:23744
	v_exp_f32_e32 v4, v85
	ds_read_b64_tr_b16 v[114:115], v244 offset:26304
	v_add_f32_e32 v0, v4, v0
	v_cvt_pk_bf16_f32 v4, v5, v4
	v_max3_f32 v5, v14, v165, v149
	s_waitcnt lgkmcnt(2)
	v_mfma_f32_32x32x16_bf16 v[32:47], v[80:83], v[184:187], v[32:47]
	ds_read_b64_tr_b16 v[116:117], v244 offset:28672
	ds_read_b64_tr_b16 v[118:119], v244 offset:31232
	v_exp_f32_e32 v14, v86
	v_max3_f32 v15, v5, v166, v150
	v_add_f32_e32 v0, v14, v0
	s_waitcnt lgkmcnt(2)
	v_mfma_f32_32x32x16_bf16 v[16:31], v[112:115], v[184:187], v[16:31]
	ds_read_b64_tr_b16 v[80:81], v244 offset:28736
	v_exp_f32_e32 v5, v87
	ds_read_b64_tr_b16 v[82:83], v244 offset:31296
	v_add_f32_e32 v0, v5, v0
	v_cvt_pk_bf16_f32 v5, v14, v5
	v_max3_f32 v14, v15, v167, v151
	s_waitcnt lgkmcnt(2)
	v_mfma_f32_32x32x16_bf16 v[64:79], v[116:119], v[176:179], v[64:79]
	ds_read_b64_tr_b16 v[84:85], v244 offset:28800
	ds_read_b64_tr_b16 v[86:87], v244 offset:31360
	v_exp_f32_e32 v15, v88
	v_max3_f32 v14, v14, v168, v152
	v_add_f32_e32 v0, v15, v0
	s_waitcnt lgkmcnt(2)
	v_mfma_f32_32x32x16_bf16 v[48:63], v[80:83], v[176:179], v[48:63]
	ds_read_b64_tr_b16 v[112:113], v244 offset:28864
	ds_read_b64_tr_b16 v[114:115], v244 offset:31424
	v_exp_f32_e32 v80, v89
	v_max3_f32 v14, v14, v169, v153
	v_add_f32_e32 v0, v80, v0
	v_cvt_pk_bf16_f32 v192, v15, v80
	s_waitcnt lgkmcnt(2)
	v_mfma_f32_32x32x16_bf16 v[32:47], v[84:87], v[176:179], v[32:47]
	ds_read_b64_tr_b16 v[80:81], v244 offset:33792
	ds_read_b64_tr_b16 v[82:83], v244 offset:36352
	v_exp_f32_e32 v15, v90
	v_max3_f32 v14, v14, v170, v154
	v_add_f32_e32 v0, v15, v0
	s_waitcnt lgkmcnt(2)
	v_mfma_f32_32x32x16_bf16 v[16:31], v[112:115], v[176:179], v[16:31]
	ds_read_b64_tr_b16 v[84:85], v244 offset:33856
	ds_read_b64_tr_b16 v[86:87], v244 offset:36416
	v_exp_f32_e32 v88, v91
	v_max3_f32 v14, v14, v171, v155
	v_add_f32_e32 v0, v88, v0
	v_cvt_pk_bf16_f32 v193, v15, v88
	s_waitcnt lgkmcnt(2)
	v_mfma_f32_32x32x16_bf16 v[64:79], v[80:83], v[180:183], v[64:79]
	ds_read_b64_tr_b16 v[88:89], v244 offset:33920
	ds_read_b64_tr_b16 v[90:91], v244 offset:36480
	v_exp_f32_e32 v15, v92
	v_max3_f32 v14, v14, v172, v156
	v_add_f32_e32 v0, v15, v0
	s_waitcnt lgkmcnt(2)
	v_mfma_f32_32x32x16_bf16 v[48:63], v[84:87], v[180:183], v[48:63]
	ds_read_b64_tr_b16 v[80:81], v244 offset:33984
	ds_read_b64_tr_b16 v[82:83], v244 offset:36544
	v_exp_f32_e32 v84, v93
	v_max3_f32 v14, v14, v173, v157
	v_add_f32_e32 v0, v84, v0
	v_cvt_pk_bf16_f32 v194, v15, v84
	s_waitcnt lgkmcnt(2)
	v_mfma_f32_32x32x16_bf16 v[32:47], v[88:91], v[180:183], v[32:47]
	v_exp_f32_e32 v15, v94
	v_max3_f32 v14, v14, v174, v158
	v_add_f32_e32 v0, v15, v0
	s_waitcnt lgkmcnt(0)
	v_mfma_f32_32x32x16_bf16 v[16:31], v[80:83], v[180:183], v[16:31]
	v_exp_f32_e32 v80, v95
	s_nop 0
	v_add_f32_e32 v0, v80, v0
	v_cvt_pk_bf16_f32 v195, v15, v80
	v_max3_f32 v15, v14, v175, v159
	v_mov_b32_e32 v14, v0
	v_cmp_gt_f32_e32 vcc, 1.0, v226
	s_nop 0
	v_permlane32_swap_b32_e32 v0, v14
	s_cbranch_vccz .LBB0_565
	v_pk_mul_f32 v[78:79], v[226:227], v[78:79] op_sel_hi:[0,1]
	v_pk_mul_f32 v[76:77], v[226:227], v[76:77] op_sel_hi:[0,1]
	v_pk_mul_f32 v[74:75], v[226:227], v[74:75] op_sel_hi:[0,1]
	v_pk_mul_f32 v[72:73], v[226:227], v[72:73] op_sel_hi:[0,1]
	v_pk_mul_f32 v[70:71], v[226:227], v[70:71] op_sel_hi:[0,1]
	v_pk_mul_f32 v[68:69], v[226:227], v[68:69] op_sel_hi:[0,1]
	v_pk_mul_f32 v[66:67], v[226:227], v[66:67] op_sel_hi:[0,1]
	v_pk_mul_f32 v[64:65], v[226:227], v[64:65] op_sel_hi:[0,1]
	v_pk_mul_f32 v[62:63], v[226:227], v[62:63] op_sel_hi:[0,1]
	v_pk_mul_f32 v[60:61], v[226:227], v[60:61] op_sel_hi:[0,1]
	v_pk_mul_f32 v[58:59], v[226:227], v[58:59] op_sel_hi:[0,1]
	v_pk_mul_f32 v[56:57], v[226:227], v[56:57] op_sel_hi:[0,1]
	v_pk_mul_f32 v[54:55], v[226:227], v[54:55] op_sel_hi:[0,1]
	v_pk_mul_f32 v[52:53], v[226:227], v[52:53] op_sel_hi:[0,1]
	v_pk_mul_f32 v[50:51], v[226:227], v[50:51] op_sel_hi:[0,1]
	v_pk_mul_f32 v[48:49], v[226:227], v[48:49] op_sel_hi:[0,1]
	v_pk_mul_f32 v[46:47], v[226:227], v[46:47] op_sel_hi:[0,1]
	v_pk_mul_f32 v[44:45], v[226:227], v[44:45] op_sel_hi:[0,1]
	v_pk_mul_f32 v[42:43], v[226:227], v[42:43] op_sel_hi:[0,1]
	v_pk_mul_f32 v[40:41], v[226:227], v[40:41] op_sel_hi:[0,1]
	v_pk_mul_f32 v[38:39], v[226:227], v[38:39] op_sel_hi:[0,1]
	v_pk_mul_f32 v[36:37], v[226:227], v[36:37] op_sel_hi:[0,1]
	v_pk_mul_f32 v[34:35], v[226:227], v[34:35] op_sel_hi:[0,1]
	v_pk_mul_f32 v[32:33], v[226:227], v[32:33] op_sel_hi:[0,1]
	v_pk_mul_f32 v[30:31], v[226:227], v[30:31] op_sel_hi:[0,1]
	v_pk_mul_f32 v[28:29], v[226:227], v[28:29] op_sel_hi:[0,1]
	v_pk_mul_f32 v[26:27], v[226:227], v[26:27] op_sel_hi:[0,1]
	v_pk_mul_f32 v[24:25], v[226:227], v[24:25] op_sel_hi:[0,1]
	v_pk_mul_f32 v[22:23], v[226:227], v[22:23] op_sel_hi:[0,1]
	v_pk_mul_f32 v[20:21], v[226:227], v[20:21] op_sel_hi:[0,1]
	v_pk_mul_f32 v[18:19], v[226:227], v[18:19] op_sel_hi:[0,1]
	v_pk_mul_f32 v[16:17], v[226:227], v[16:17] op_sel_hi:[0,1]

.LBB0_568:
	s_min_u32 s34, s12, s4
	s_waitcnt vmcnt(2)
	ds_write_b128 v241, v[196:199] offset:9216
	s_waitcnt vmcnt(1)
	ds_write_b128 v240, v[200:203] offset:38912
	s_waitcnt vmcnt(0)
	ds_write_b128 v240, v[204:207] offset:49152
	s_lshl_b64 s[30:31], s[34:35], 13
	s_waitcnt lgkmcnt(0)
	s_barrier
	v_lshl_add_u64 v[80:81], v[224:225], 0, s[30:31]
	global_load_dwordx4 v[196:199], v[80:81], off
	global_load_dwordx4 v[200:203], v[218:219], off offset:-4096
	global_load_dwordx4 v[204:207], v[218:219], off
	ds_read_b128 v[176:179], v243 offset:13824
	ds_read_b128 v[80:83], v243 offset:9216
	ds_read_b128 v[180:183], v242 offset:59392
	s_waitcnt lgkmcnt(0)
	v_mfma_f32_32x32x16_bf16 v[128:143], v[80:83], v[180:183], v[112:127]
	ds_read_b128 v[184:187], v243 offset:9248
	ds_read_b128 v[248:251], v242 offset:60416
	v_exp_f32_e32 v15, v160
	v_exp_f32_e32 v80, v161
	v_add_f32_e32 v81, 0, v15
	v_add_f32_e32 v81, v80, v81
	v_cvt_pk_bf16_f32 v188, v15, v80
	v_exp_f32_e32 v15, v162
	v_exp_f32_e32 v80, v163
	ds_read_b128 v[160:163], v243 offset:13856
	v_add_f32_e32 v81, v15, v81
	v_cvt_pk_bf16_f32 v189, v15, v80
	v_add_f32_e32 v15, v80, v81
	v_mfma_f32_32x32x16_bf16 v[80:95], v[176:179], v[180:183], v[112:127]
	s_waitcnt lgkmcnt(1)
	v_mfma_f32_32x32x16_bf16 v[128:143], v[184:187], v[248:251], v[128:143]
	ds_read_b128 v[176:179], v243 offset:9280
	ds_read_b128 v[180:183], v242 offset:61440
	v_exp_f32_e32 v164, v164
	v_exp_f32_e32 v165, v165
	v_add_f32_e32 v15, v164, v15
	v_cvt_pk_bf16_f32 v190, v164, v165
	v_add_f32_e32 v15, v165, v15
	s_waitcnt lgkmcnt(2)
	v_mfma_f32_32x32x16_bf16 v[80:95], v[160:163], v[248:251], v[80:95]
	ds_read_b128 v[234:237], v243 offset:13888
	v_exp_f32_e32 v160, v166
	v_exp_f32_e32 v161, v167
	v_add_f32_e32 v15, v160, v15
	v_cvt_pk_bf16_f32 v191, v160, v161
	v_add_f32_e32 v15, v161, v15
	s_waitcnt lgkmcnt(1)
	v_mfma_f32_32x32x16_bf16 v[128:143], v[176:179], v[180:183], v[128:143]
	ds_read_b128 v[160:163], v243 offset:9312
	ds_read_b128 v[164:167], v242 offset:62464
	v_exp_f32_e32 v168, v168
	v_exp_f32_e32 v169, v169
	v_add_f32_e32 v15, v168, v15
	v_cvt_pk_bf16_f32 v184, v168, v169
	v_add_f32_e32 v15, v169, v15
	s_waitcnt lgkmcnt(2)
	v_mfma_f32_32x32x16_bf16 v[80:95], v[234:237], v[180:183], v[80:95]
	ds_read_b128 v[176:179], v243 offset:13920
	v_exp_f32_e32 v168, v170
	v_exp_f32_e32 v169, v171
	v_add_f32_e32 v15, v168, v15
	v_cvt_pk_bf16_f32 v185, v168, v169
	v_add_f32_e32 v15, v169, v15
	s_waitcnt lgkmcnt(1)
	v_mfma_f32_32x32x16_bf16 v[128:143], v[160:163], v[164:167], v[128:143]
	ds_read_b64_tr_b16 v[168:169], v244 offset:38912
	ds_read_b64_tr_b16 v[170:171], v244 offset:41472
	v_exp_f32_e32 v160, v172
	v_exp_f32_e32 v161, v173
	v_add_f32_e32 v15, v160, v15
	v_cvt_pk_bf16_f32 v186, v160, v161
	v_add_f32_e32 v15, v161, v15
	s_waitcnt lgkmcnt(2)
	v_mfma_f32_32x32x16_bf16 v[80:95], v[176:179], v[164:167], v[80:95]
	ds_read_b64_tr_b16 v[160:161], v244 offset:38976
	ds_read_b64_tr_b16 v[162:163], v244 offset:41536
	v_exp_f32_e32 v172, v174
	v_exp_f32_e32 v173, v175
	v_add_f32_e32 v15, v172, v15
	v_cvt_pk_bf16_f32 v187, v172, v173
	v_add_f32_e32 v15, v173, v15
	s_waitcnt lgkmcnt(2)
	v_mfma_f32_32x32x16_bf16 v[64:79], v[168:171], v[10:13], v[64:79]
	ds_read_b64_tr_b16 v[164:165], v244 offset:39040
	ds_read_b64_tr_b16 v[166:167], v244 offset:41600
	v_exp_f32_e32 v144, v144
	v_max3_f32 v172, v128, s33, v80
	v_add_f32_e32 v15, v144, v15
	s_waitcnt lgkmcnt(2)
	v_mfma_f32_32x32x16_bf16 v[48:63], v[160:163], v[10:13], v[48:63]
	ds_read_b64_tr_b16 v[168:169], v244 offset:39104
	v_exp_f32_e32 v145, v145
	ds_read_b64_tr_b16 v[170:171], v244 offset:41664
	v_cvt_pk_bf16_f32 v176, v144, v145
	v_max3_f32 v144, v172, v129, v81
	v_add_f32_e32 v15, v145, v15
	s_waitcnt lgkmcnt(2)
	v_mfma_f32_32x32x16_bf16 v[32:47], v[164:167], v[10:13], v[32:47]
	ds_read_b64_tr_b16 v[160:161], v244 offset:44032
	ds_read_b64_tr_b16 v[162:163], v244 offset:46592
	v_exp_f32_e32 v145, v146
	v_max3_f32 v144, v144, v130, v82
	v_add_f32_e32 v15, v145, v15
	s_waitcnt lgkmcnt(2)
	v_mfma_f32_32x32x16_bf16 v[16:31], v[168:171], v[10:13], v[16:31]
	ds_read_b64_tr_b16 v[164:165], v244 offset:44096
	ds_read_b64_tr_b16 v[166:167], v244 offset:46656
	v_exp_f32_e32 v10, v147
	v_max3_f32 v144, v144, v131, v83
	v_cvt_pk_bf16_f32 v177, v145, v10
	v_add_f32_e32 v15, v10, v15
	s_waitcnt lgkmcnt(2)
	v_mfma_f32_32x32x16_bf16 v[64:79], v[160:163], v[6:9], v[64:79]
	ds_read_b64_tr_b16 v[10:11], v244 offset:44160
	ds_read_b64_tr_b16 v[12:13], v244 offset:46720
	v_exp_f32_e32 v148, v148
	v_max3_f32 v160, v144, v132, v84
	v_add_f32_e32 v15, v148, v15
	s_waitcnt lgkmcnt(2)
	v_mfma_f32_32x32x16_bf16 v[48:63], v[164:167], v[6:9], v[48:63]
	ds_read_b64_tr_b16 v[144:145], v244 offset:44224
	v_exp_f32_e32 v149, v149
	ds_read_b64_tr_b16 v[146:147], v244 offset:46784
	v_cvt_pk_bf16_f32 v178, v148, v149
	v_max3_f32 v148, v160, v133, v85
	v_add_f32_e32 v15, v149, v15
	s_waitcnt lgkmcnt(2)
	v_mfma_f32_32x32x16_bf16 v[32:47], v[10:13], v[6:9], v[32:47]
	ds_read_b64_tr_b16 v[160:161], v244 offset:49152
	ds_read_b64_tr_b16 v[162:163], v244 offset:51712
	v_exp_f32_e32 v149, v150
	v_max3_f32 v148, v148, v134, v86
	v_add_f32_e32 v15, v149, v15
	s_waitcnt lgkmcnt(2)
	v_mfma_f32_32x32x16_bf16 v[16:31], v[144:147], v[6:9], v[16:31]
	ds_read_b64_tr_b16 v[10:11], v244 offset:49216
	ds_read_b64_tr_b16 v[12:13], v244 offset:51776
	v_exp_f32_e32 v6, v151
	v_max3_f32 v144, v148, v135, v87
	v_cvt_pk_bf16_f32 v179, v149, v6
	v_add_f32_e32 v15, v6, v15
	s_waitcnt lgkmcnt(2)
	v_mfma_f32_32x32x16_bf16 v[64:79], v[160:163], v[2:5], v[64:79]
	ds_read_b64_tr_b16 v[6:7], v244 offset:49280
	ds_read_b64_tr_b16 v[8:9], v244 offset:51840
	v_exp_f32_e32 v148, v152
	v_max3_f32 v149, v144, v136, v88
	v_add_f32_e32 v15, v148, v15
	s_waitcnt lgkmcnt(2)
	v_mfma_f32_32x32x16_bf16 v[48:63], v[10:13], v[2:5], v[48:63]
	ds_read_b64_tr_b16 v[144:145], v244 offset:49344
	v_exp_f32_e32 v10, v153
	ds_read_b64_tr_b16 v[146:147], v244 offset:51904
	v_cvt_pk_bf16_f32 v180, v148, v10
	v_max3_f32 v148, v149, v137, v89
	v_add_f32_e32 v15, v10, v15
	s_waitcnt lgkmcnt(2)
	v_mfma_f32_32x32x16_bf16 v[32:47], v[6:9], v[2:5], v[32:47]
	ds_read_b64_tr_b16 v[10:11], v244 offset:54272
	ds_read_b64_tr_b16 v[12:13], v244 offset:56832
	v_exp_f32_e32 v149, v154
	v_max3_f32 v148, v148, v138, v90
	v_add_f32_e32 v15, v149, v15
	s_waitcnt lgkmcnt(2)
	v_mfma_f32_32x32x16_bf16 v[16:31], v[144:147], v[2:5], v[16:31]
	ds_read_b64_tr_b16 v[6:7], v244 offset:54336
	ds_read_b64_tr_b16 v[8:9], v244 offset:56896
	v_exp_f32_e32 v2, v155
	v_max3_f32 v144, v148, v139, v91
	v_cvt_pk_bf16_f32 v181, v149, v2
	v_add_f32_e32 v15, v2, v15
	s_waitcnt lgkmcnt(2)
	v_mfma_f32_32x32x16_bf16 v[64:79], v[10:13], v[192:195], v[64:79]
	ds_read_b64_tr_b16 v[2:3], v244 offset:54400
	ds_read_b64_tr_b16 v[4:5], v244 offset:56960
	v_exp_f32_e32 v145, v156
	v_max3_f32 v144, v144, v140, v92
	v_add_f32_e32 v15, v145, v15
	s_waitcnt lgkmcnt(2)
	v_mfma_f32_32x32x16_bf16 v[48:63], v[6:9], v[192:195], v[48:63]
	ds_read_b64_tr_b16 v[10:11], v244 offset:54464
	v_exp_f32_e32 v6, v157
	ds_read_b64_tr_b16 v[12:13], v244 offset:57024
	v_add_f32_e32 v7, v6, v15
	v_cvt_pk_bf16_f32 v182, v145, v6
	v_max3_f32 v6, v144, v141, v93
	s_waitcnt lgkmcnt(2)
	v_mfma_f32_32x32x16_bf16 v[32:47], v[2:5], v[192:195], v[32:47]
	v_exp_f32_e32 v3, v158
	v_max3_f32 v4, v6, v142, v94
	v_add_f32_e32 v2, v3, v7
	s_waitcnt lgkmcnt(0)
	v_mfma_f32_32x32x16_bf16 v[16:31], v[10:13], v[192:195], v[16:31]
	v_exp_f32_e32 v5, v159
	s_nop 0
	v_add_f32_e32 v2, v5, v2
	v_cvt_pk_bf16_f32 v183, v3, v5
	v_max3_f32 v3, v4, v143, v95
	v_mov_b32_e32 v4, v2
	v_cmp_gt_f32_e32 vcc, 1.0, v0
	s_nop 0
	v_permlane32_swap_b32_e32 v2, v4
	s_cbranch_vccz .LBB0_570
	v_pk_mul_f32 v[78:79], v[0:1], v[78:79] op_sel_hi:[0,1]
	v_pk_mul_f32 v[76:77], v[0:1], v[76:77] op_sel_hi:[0,1]
	v_pk_mul_f32 v[74:75], v[0:1], v[74:75] op_sel_hi:[0,1]
	v_pk_mul_f32 v[72:73], v[0:1], v[72:73] op_sel_hi:[0,1]
	v_pk_mul_f32 v[70:71], v[0:1], v[70:71] op_sel_hi:[0,1]
	v_pk_mul_f32 v[68:69], v[0:1], v[68:69] op_sel_hi:[0,1]
	v_pk_mul_f32 v[66:67], v[0:1], v[66:67] op_sel_hi:[0,1]
	v_pk_mul_f32 v[64:65], v[0:1], v[64:65] op_sel_hi:[0,1]
	v_pk_mul_f32 v[62:63], v[0:1], v[62:63] op_sel_hi:[0,1]
	v_pk_mul_f32 v[60:61], v[0:1], v[60:61] op_sel_hi:[0,1]
	v_pk_mul_f32 v[58:59], v[0:1], v[58:59] op_sel_hi:[0,1]
	v_pk_mul_f32 v[56:57], v[0:1], v[56:57] op_sel_hi:[0,1]
	v_pk_mul_f32 v[54:55], v[0:1], v[54:55] op_sel_hi:[0,1]
	v_pk_mul_f32 v[52:53], v[0:1], v[52:53] op_sel_hi:[0,1]
	v_pk_mul_f32 v[50:51], v[0:1], v[50:51] op_sel_hi:[0,1]
	v_pk_mul_f32 v[48:49], v[0:1], v[48:49] op_sel_hi:[0,1]
	v_pk_mul_f32 v[46:47], v[0:1], v[46:47] op_sel_hi:[0,1]
	v_pk_mul_f32 v[44:45], v[0:1], v[44:45] op_sel_hi:[0,1]
	v_pk_mul_f32 v[42:43], v[0:1], v[42:43] op_sel_hi:[0,1]
	v_pk_mul_f32 v[40:41], v[0:1], v[40:41] op_sel_hi:[0,1]
	v_pk_mul_f32 v[38:39], v[0:1], v[38:39] op_sel_hi:[0,1]
	v_pk_mul_f32 v[36:37], v[0:1], v[36:37] op_sel_hi:[0,1]
	v_pk_mul_f32 v[34:35], v[0:1], v[34:35] op_sel_hi:[0,1]
	v_pk_mul_f32 v[32:33], v[0:1], v[32:33] op_sel_hi:[0,1]
	v_pk_mul_f32 v[30:31], v[0:1], v[30:31] op_sel_hi:[0,1]
	v_pk_mul_f32 v[28:29], v[0:1], v[28:29] op_sel_hi:[0,1]
	v_pk_mul_f32 v[26:27], v[0:1], v[26:27] op_sel_hi:[0,1]
	v_pk_mul_f32 v[24:25], v[0:1], v[24:25] op_sel_hi:[0,1]
	v_pk_mul_f32 v[22:23], v[0:1], v[22:23] op_sel_hi:[0,1]
	v_pk_mul_f32 v[20:21], v[0:1], v[20:21] op_sel_hi:[0,1]
	v_pk_mul_f32 v[18:19], v[0:1], v[18:19] op_sel_hi:[0,1]
	v_pk_mul_f32 v[16:17], v[0:1], v[16:17] op_sel_hi:[0,1]
.LBB0_570:
	v_add_f32_e32 v0, v2, v4
	v_add_f32_e32 v248, v14, v0
	v_mov_b32_e32 v0, v3
	s_cmp_ge_u32 s13, s16
	v_mov_b32_e32 v226, 1.0
	v_permlane32_swap_b32_e32 v3, v0
	s_cbranch_scc1 .LBB0_574
	v_max_f32_e32 v2, v3, v3
	v_max_f32_e32 v0, v0, v0
	v_max_f32_e32 v0, v2, v0
	v_cmp_lt_f32_e32 vcc, s28, v0
	s_cbranch_vccz .LBB0_573
	v_max_f32_e32 v0, v0, v0
	v_max_f32_e32 v0, 0, v0
	v_exp_f32_e64 v226, -v0
	v_add_f32_e32 v247, v247, v0
	v_xor_b32_e32 v112, 0x80000000, v247
	v_sub_f32_e32 v143, v143, v0
	v_sub_f32_e32 v142, v142, v0
	v_sub_f32_e32 v141, v141, v0
	v_sub_f32_e32 v140, v140, v0
	v_sub_f32_e32 v139, v139, v0
	v_sub_f32_e32 v138, v138, v0
	v_sub_f32_e32 v137, v137, v0
	v_sub_f32_e32 v136, v136, v0
	v_sub_f32_e32 v135, v135, v0
	v_sub_f32_e32 v134, v134, v0
	v_sub_f32_e32 v133, v133, v0
	v_sub_f32_e32 v132, v132, v0
	v_sub_f32_e32 v131, v131, v0
	v_sub_f32_e32 v130, v130, v0
	v_sub_f32_e32 v129, v129, v0
	v_sub_f32_e32 v128, v128, v0
	v_sub_f32_e32 v95, v95, v0
	v_sub_f32_e32 v94, v94, v0
	v_sub_f32_e32 v93, v93, v0
	v_sub_f32_e32 v92, v92, v0
	v_sub_f32_e32 v91, v91, v0
	v_sub_f32_e32 v90, v90, v0
	v_sub_f32_e32 v89, v89, v0
	v_sub_f32_e32 v88, v88, v0
	v_sub_f32_e32 v87, v87, v0
	v_sub_f32_e32 v86, v86, v0
	v_sub_f32_e32 v85, v85, v0
	v_sub_f32_e32 v84, v84, v0
	v_sub_f32_e32 v83, v83, v0
	v_sub_f32_e32 v82, v82, v0
	v_sub_f32_e32 v81, v81, v0
	v_sub_f32_e32 v80, v80, v0
	v_mul_f32_e32 v248, v248, v226
	v_mov_b32_e32 v113, v112
	v_mov_b32_e32 v114, v112
	v_mov_b32_e32 v115, v112
	v_mov_b32_e32 v116, v112
	v_mov_b32_e32 v117, v112
	v_mov_b32_e32 v118, v112
	v_mov_b32_e32 v119, v112
	v_mov_b32_e32 v120, v112
	v_mov_b32_e32 v121, v112
	v_mov_b32_e32 v122, v112
	v_mov_b32_e32 v123, v112
	v_mov_b32_e32 v124, v112
	v_mov_b32_e32 v125, v112
	v_mov_b32_e32 v126, v112
	v_mov_b32_e32 v127, v112
	v_mov_b32_e32 v111, v112
	v_mov_b32_e32 v110, v112
	v_mov_b32_e32 v109, v112
	v_mov_b32_e32 v108, v112
	v_mov_b32_e32 v107, v112
	v_mov_b32_e32 v106, v112
	v_mov_b32_e32 v105, v112
	v_mov_b32_e32 v104, v112
	v_mov_b32_e32 v103, v112
	v_mov_b32_e32 v102, v112
	v_mov_b32_e32 v101, v112
	v_mov_b32_e32 v100, v112
	v_mov_b32_e32 v99, v112
	v_mov_b32_e32 v98, v112
	v_mov_b32_e32 v97, v112
	v_mov_b32_e32 v96, v112
	s_branch .LBB0_574

.LBB0_582:
	s_add_i32 s13, s12, -1
	s_min_u32 s34, s13, s4
	s_lshl_b64 s[30:31], s[34:35], 13
	v_lshl_add_u64 v[2:3], v[216:217], 0, s[30:31]
	global_load_dwordx4 v[196:199], v[2:3], off
	v_add_co_u32_e32 v2, vcc, s1, v212
	s_nop 1
	v_addc_co_u32_e32 v3, vcc, -1, v213, vcc
	global_load_dwordx4 v[200:203], v[2:3], off offset:-4096
	global_load_dwordx4 v[204:207], v[2:3], off
	ds_read_b128 v[2:5], v243 offset:4608
	ds_read_b128 v[6:9], v243
	ds_read_b128 v[12:15], v242 offset:59392
	s_waitcnt lgkmcnt(0)
	v_mfma_f32_32x32x16_bf16 v[160:175], v[6:9], v[12:15], v[96:111]
	ds_read_b128 v[112:115], v243 offset:32
	ds_read_b128 v[116:119], v242 offset:60416
	v_exp_f32_e32 v0, v128
	v_exp_f32_e32 v6, v129
	v_add_f32_e32 v7, 0, v0
	v_add_f32_e32 v11, v6, v7
	v_cvt_pk_bf16_f32 v10, v0, v6
	v_mfma_f32_32x32x16_bf16 v[144:159], v[2:5], v[12:15], v[96:111]
	ds_read_b128 v[6:9], v243 offset:4640
	v_exp_f32_e32 v0, v130
	v_exp_f32_e32 v120, v131
	v_add_f32_e32 v121, v0, v11
	v_cvt_pk_bf16_f32 v11, v0, v120
	v_add_f32_e32 v0, v120, v121
	s_waitcnt lgkmcnt(1)
	v_mfma_f32_32x32x16_bf16 v[160:175], v[112:115], v[116:119], v[160:175]
	ds_read_b128 v[2:5], v243 offset:64
	ds_read_b128 v[120:123], v242 offset:61440
	v_exp_f32_e32 v12, v132
	v_exp_f32_e32 v13, v133
	v_add_f32_e32 v0, v12, v0
	v_add_f32_e32 v0, v13, v0
	v_cvt_pk_bf16_f32 v12, v12, v13
	s_waitcnt lgkmcnt(2)
	v_mfma_f32_32x32x16_bf16 v[144:159], v[6:9], v[116:119], v[144:159]
	ds_read_b128 v[112:115], v243 offset:4672
	v_exp_f32_e32 v6, v134
	v_exp_f32_e32 v7, v135
	v_add_f32_e32 v0, v6, v0
	v_add_f32_e32 v0, v7, v0
	v_cvt_pk_bf16_f32 v13, v6, v7
	s_waitcnt lgkmcnt(1)
	v_mfma_f32_32x32x16_bf16 v[160:175], v[2:5], v[120:123], v[160:175]
	ds_read_b128 v[116:119], v243 offset:96
	ds_read_b128 v[124:127], v242 offset:62464
	v_exp_f32_e32 v2, v136
	v_exp_f32_e32 v3, v137
	v_add_f32_e32 v0, v2, v0
	v_add_f32_e32 v0, v3, v0
	v_cvt_pk_bf16_f32 v6, v2, v3
	s_waitcnt lgkmcnt(2)
	v_mfma_f32_32x32x16_bf16 v[144:159], v[112:115], v[120:123], v[144:159]
	ds_read_b128 v[2:5], v243 offset:4704
	v_exp_f32_e32 v7, v138
	v_exp_f32_e32 v8, v139
	v_add_f32_e32 v0, v7, v0
	v_add_f32_e32 v0, v8, v0
	v_cvt_pk_bf16_f32 v7, v7, v8
	s_waitcnt lgkmcnt(1)
	v_mfma_f32_32x32x16_bf16 v[160:175], v[116:119], v[124:127], v[160:175]
	ds_read_b64_tr_b16 v[112:113], v244 offset:18432
	ds_read_b64_tr_b16 v[114:115], v244 offset:20992
	v_exp_f32_e32 v8, v140
	v_exp_f32_e32 v9, v141
	v_add_f32_e32 v0, v8, v0
	v_add_f32_e32 v0, v9, v0
	v_cvt_pk_bf16_f32 v8, v8, v9
	s_waitcnt lgkmcnt(2)
	v_mfma_f32_32x32x16_bf16 v[144:159], v[2:5], v[124:127], v[144:159]
	ds_read_b64_tr_b16 v[116:117], v244 offset:18496
	ds_read_b64_tr_b16 v[118:119], v244 offset:21056
	v_exp_f32_e32 v9, v142
	v_exp_f32_e32 v14, v143
	v_add_f32_e32 v0, v9, v0
	v_add_f32_e32 v0, v14, v0
	v_cvt_pk_bf16_f32 v9, v9, v14
	s_waitcnt lgkmcnt(2)
	v_mfma_f32_32x32x16_bf16 v[64:79], v[112:115], v[188:191], v[64:79]
	ds_read_b64_tr_b16 v[120:121], v244 offset:18560
	ds_read_b64_tr_b16 v[122:123], v244 offset:21120
	v_exp_f32_e32 v2, v80
	v_max3_f32 v3, v160, s33, v144
	v_add_f32_e32 v0, v2, v0
	s_waitcnt lgkmcnt(2)
	v_mfma_f32_32x32x16_bf16 v[48:63], v[116:119], v[188:191], v[48:63]
	ds_read_b64_tr_b16 v[112:113], v244 offset:18624
	ds_read_b64_tr_b16 v[114:115], v244 offset:21184
	v_exp_f32_e32 v4, v81
	v_max3_f32 v3, v3, v161, v145
	v_add_f32_e32 v0, v4, v0
	v_cvt_pk_bf16_f32 v2, v2, v4
	s_waitcnt lgkmcnt(2)
	v_mfma_f32_32x32x16_bf16 v[32:47], v[120:123], v[188:191], v[32:47]
	ds_read_b64_tr_b16 v[116:117], v244 offset:23552
	ds_read_b64_tr_b16 v[118:119], v244 offset:26112
	v_exp_f32_e32 v4, v82
	v_max3_f32 v5, v3, v162, v146
	v_add_f32_e32 v0, v4, v0
	s_waitcnt lgkmcnt(2)
	v_mfma_f32_32x32x16_bf16 v[16:31], v[112:115], v[188:191], v[16:31]
	ds_read_b64_tr_b16 v[120:121], v244 offset:23616
	v_exp_f32_e32 v3, v83
	ds_read_b64_tr_b16 v[122:123], v244 offset:26176
	v_add_f32_e32 v0, v3, v0
	v_cvt_pk_bf16_f32 v3, v4, v3
	v_max3_f32 v4, v5, v163, v147
	s_waitcnt lgkmcnt(2)
	v_mfma_f32_32x32x16_bf16 v[64:79], v[116:119], v[184:187], v[64:79]
	ds_read_b64_tr_b16 v[80:81], v244 offset:23680
	ds_read_b64_tr_b16 v[82:83], v244 offset:26240
	v_exp_f32_e32 v5, v84
	v_max3_f32 v14, v4, v164, v148
	v_add_f32_e32 v0, v5, v0
	s_waitcnt lgkmcnt(2)
	v_mfma_f32_32x32x16_bf16 v[48:63], v[120:123], v[184:187], v[48:63]
	ds_read_b64_tr_b16 v[112:113], v244 offset:23744
	v_exp_f32_e32 v4, v85
	ds_read_b64_tr_b16 v[114:115], v244 offset:26304
	v_add_f32_e32 v0, v4, v0
	v_cvt_pk_bf16_f32 v4, v5, v4
	v_max3_f32 v5, v14, v165, v149
	s_waitcnt lgkmcnt(2)
	v_mfma_f32_32x32x16_bf16 v[32:47], v[80:83], v[184:187], v[32:47]
	ds_read_b64_tr_b16 v[116:117], v244 offset:28672
	ds_read_b64_tr_b16 v[118:119], v244 offset:31232
	v_exp_f32_e32 v14, v86
	v_max3_f32 v15, v5, v166, v150
	v_add_f32_e32 v0, v14, v0
	s_waitcnt lgkmcnt(2)
	v_mfma_f32_32x32x16_bf16 v[16:31], v[112:115], v[184:187], v[16:31]
	ds_read_b64_tr_b16 v[80:81], v244 offset:28736
	v_exp_f32_e32 v5, v87
	ds_read_b64_tr_b16 v[82:83], v244 offset:31296
	v_add_f32_e32 v0, v5, v0
	v_cvt_pk_bf16_f32 v5, v14, v5
	v_max3_f32 v14, v15, v167, v151
	s_waitcnt lgkmcnt(2)
	v_mfma_f32_32x32x16_bf16 v[64:79], v[116:119], v[176:179], v[64:79]
	ds_read_b64_tr_b16 v[84:85], v244 offset:28800
	ds_read_b64_tr_b16 v[86:87], v244 offset:31360
	v_exp_f32_e32 v15, v88
	v_max3_f32 v14, v14, v168, v152
	v_add_f32_e32 v0, v15, v0
	s_waitcnt lgkmcnt(2)
	v_mfma_f32_32x32x16_bf16 v[48:63], v[80:83], v[176:179], v[48:63]
	ds_read_b64_tr_b16 v[112:113], v244 offset:28864
	ds_read_b64_tr_b16 v[114:115], v244 offset:31424
	v_exp_f32_e32 v80, v89
	v_max3_f32 v14, v14, v169, v153
	v_add_f32_e32 v0, v80, v0
	v_cvt_pk_bf16_f32 v192, v15, v80
	s_waitcnt lgkmcnt(2)
	v_mfma_f32_32x32x16_bf16 v[32:47], v[84:87], v[176:179], v[32:47]
	ds_read_b64_tr_b16 v[80:81], v244 offset:33792
	ds_read_b64_tr_b16 v[82:83], v244 offset:36352
	v_exp_f32_e32 v15, v90
	v_max3_f32 v14, v14, v170, v154
	v_add_f32_e32 v0, v15, v0
	s_waitcnt lgkmcnt(2)
	v_mfma_f32_32x32x16_bf16 v[16:31], v[112:115], v[176:179], v[16:31]
	ds_read_b64_tr_b16 v[84:85], v244 offset:33856
	ds_read_b64_tr_b16 v[86:87], v244 offset:36416
	v_exp_f32_e32 v88, v91
	v_max3_f32 v14, v14, v171, v155
	v_add_f32_e32 v0, v88, v0
	v_cvt_pk_bf16_f32 v193, v15, v88
	s_waitcnt lgkmcnt(2)
	v_mfma_f32_32x32x16_bf16 v[64:79], v[80:83], v[180:183], v[64:79]
	ds_read_b64_tr_b16 v[88:89], v244 offset:33920
	ds_read_b64_tr_b16 v[90:91], v244 offset:36480
	v_exp_f32_e32 v15, v92
	v_max3_f32 v14, v14, v172, v156
	v_add_f32_e32 v0, v15, v0
	s_waitcnt lgkmcnt(2)
	v_mfma_f32_32x32x16_bf16 v[48:63], v[84:87], v[180:183], v[48:63]
	ds_read_b64_tr_b16 v[80:81], v244 offset:33984
	ds_read_b64_tr_b16 v[82:83], v244 offset:36544
	v_exp_f32_e32 v84, v93
	v_max3_f32 v14, v14, v173, v157
	v_add_f32_e32 v0, v84, v0
	v_cvt_pk_bf16_f32 v194, v15, v84
	s_waitcnt lgkmcnt(2)
	v_mfma_f32_32x32x16_bf16 v[32:47], v[88:91], v[180:183], v[32:47]
	v_exp_f32_e32 v15, v94
	v_max3_f32 v14, v14, v174, v158
	v_add_f32_e32 v0, v15, v0
	s_waitcnt lgkmcnt(0)
	v_mfma_f32_32x32x16_bf16 v[16:31], v[80:83], v[180:183], v[16:31]
	v_exp_f32_e32 v80, v95
	s_nop 0
	v_add_f32_e32 v0, v80, v0
	v_cvt_pk_bf16_f32 v195, v15, v80
	v_max3_f32 v15, v14, v175, v159
	v_mov_b32_e32 v14, v0
	v_cmp_gt_f32_e32 vcc, 1.0, v220
	s_nop 0
	v_permlane32_swap_b32_e32 v0, v14
	s_cbranch_vccz .LBB0_584
	v_pk_mul_f32 v[78:79], v[220:221], v[78:79] op_sel_hi:[0,1]
	v_pk_mul_f32 v[76:77], v[220:221], v[76:77] op_sel_hi:[0,1]
	v_pk_mul_f32 v[74:75], v[220:221], v[74:75] op_sel_hi:[0,1]
	v_pk_mul_f32 v[72:73], v[220:221], v[72:73] op_sel_hi:[0,1]
	v_pk_mul_f32 v[70:71], v[220:221], v[70:71] op_sel_hi:[0,1]
	v_pk_mul_f32 v[68:69], v[220:221], v[68:69] op_sel_hi:[0,1]
	v_pk_mul_f32 v[66:67], v[220:221], v[66:67] op_sel_hi:[0,1]
	v_pk_mul_f32 v[64:65], v[220:221], v[64:65] op_sel_hi:[0,1]
	v_pk_mul_f32 v[62:63], v[220:221], v[62:63] op_sel_hi:[0,1]
	v_pk_mul_f32 v[60:61], v[220:221], v[60:61] op_sel_hi:[0,1]
	v_pk_mul_f32 v[58:59], v[220:221], v[58:59] op_sel_hi:[0,1]
	v_pk_mul_f32 v[56:57], v[220:221], v[56:57] op_sel_hi:[0,1]
	v_pk_mul_f32 v[54:55], v[220:221], v[54:55] op_sel_hi:[0,1]
	v_pk_mul_f32 v[52:53], v[220:221], v[52:53] op_sel_hi:[0,1]
	v_pk_mul_f32 v[50:51], v[220:221], v[50:51] op_sel_hi:[0,1]
	v_pk_mul_f32 v[48:49], v[220:221], v[48:49] op_sel_hi:[0,1]
	v_pk_mul_f32 v[46:47], v[220:221], v[46:47] op_sel_hi:[0,1]
	v_pk_mul_f32 v[44:45], v[220:221], v[44:45] op_sel_hi:[0,1]
	v_pk_mul_f32 v[42:43], v[220:221], v[42:43] op_sel_hi:[0,1]
	v_pk_mul_f32 v[40:41], v[220:221], v[40:41] op_sel_hi:[0,1]
	v_pk_mul_f32 v[38:39], v[220:221], v[38:39] op_sel_hi:[0,1]
	v_pk_mul_f32 v[36:37], v[220:221], v[36:37] op_sel_hi:[0,1]
	v_pk_mul_f32 v[34:35], v[220:221], v[34:35] op_sel_hi:[0,1]
	v_pk_mul_f32 v[32:33], v[220:221], v[32:33] op_sel_hi:[0,1]
	v_pk_mul_f32 v[30:31], v[220:221], v[30:31] op_sel_hi:[0,1]
	v_pk_mul_f32 v[28:29], v[220:221], v[28:29] op_sel_hi:[0,1]
	v_pk_mul_f32 v[26:27], v[220:221], v[26:27] op_sel_hi:[0,1]
	v_pk_mul_f32 v[24:25], v[220:221], v[24:25] op_sel_hi:[0,1]
	v_pk_mul_f32 v[22:23], v[220:221], v[22:23] op_sel_hi:[0,1]
	v_pk_mul_f32 v[20:21], v[220:221], v[20:21] op_sel_hi:[0,1]
	v_pk_mul_f32 v[18:19], v[220:221], v[18:19] op_sel_hi:[0,1]
	v_pk_mul_f32 v[16:17], v[220:221], v[16:17] op_sel_hi:[0,1]

.LBB0_587:
	s_min_u32 s34, s12, s4
	s_waitcnt vmcnt(2)
	ds_write_b128 v241, v[196:199] offset:9216
	s_waitcnt vmcnt(1)
	ds_write_b128 v240, v[200:203] offset:38912
	s_waitcnt vmcnt(0)
	ds_write_b128 v240, v[204:207] offset:49152
	s_lshl_b64 s[30:31], s[34:35], 13
	s_waitcnt lgkmcnt(0)
	s_barrier
	v_lshl_add_u64 v[80:81], v[216:217], 0, s[30:31]
	global_load_dwordx4 v[196:199], v[80:81], off
	global_load_dwordx4 v[200:203], v[212:213], off offset:-4096
	global_load_dwordx4 v[204:207], v[212:213], off
	ds_read_b128 v[176:179], v243 offset:13824
	ds_read_b128 v[80:83], v243 offset:9216
	ds_read_b128 v[180:183], v242 offset:59392
	s_waitcnt lgkmcnt(0)
	v_mfma_f32_32x32x16_bf16 v[128:143], v[80:83], v[180:183], v[112:127]
	ds_read_b128 v[184:187], v243 offset:9248
	ds_read_b128 v[222:225], v242 offset:60416
	v_exp_f32_e32 v15, v160
	v_exp_f32_e32 v80, v161
	v_add_f32_e32 v81, 0, v15
	v_add_f32_e32 v81, v80, v81
	v_cvt_pk_bf16_f32 v188, v15, v80
	v_exp_f32_e32 v15, v162
	v_exp_f32_e32 v80, v163
	ds_read_b128 v[160:163], v243 offset:13856
	v_add_f32_e32 v81, v15, v81
	v_cvt_pk_bf16_f32 v189, v15, v80
	v_add_f32_e32 v15, v80, v81
	v_mfma_f32_32x32x16_bf16 v[80:95], v[176:179], v[180:183], v[112:127]
	s_waitcnt lgkmcnt(1)
	v_mfma_f32_32x32x16_bf16 v[128:143], v[184:187], v[222:225], v[128:143]
	ds_read_b128 v[176:179], v243 offset:9280
	ds_read_b128 v[180:183], v242 offset:61440
	v_exp_f32_e32 v164, v164
	v_exp_f32_e32 v165, v165
	v_add_f32_e32 v15, v164, v15
	v_cvt_pk_bf16_f32 v190, v164, v165
	v_add_f32_e32 v15, v165, v15
	s_waitcnt lgkmcnt(2)
	v_mfma_f32_32x32x16_bf16 v[80:95], v[160:163], v[222:225], v[80:95]
	ds_read_b128 v[234:237], v243 offset:13888
	v_exp_f32_e32 v160, v166
	v_exp_f32_e32 v161, v167
	v_add_f32_e32 v15, v160, v15
	v_cvt_pk_bf16_f32 v191, v160, v161
	v_add_f32_e32 v15, v161, v15
	s_waitcnt lgkmcnt(1)
	v_mfma_f32_32x32x16_bf16 v[128:143], v[176:179], v[180:183], v[128:143]
	ds_read_b128 v[160:163], v243 offset:9312
	ds_read_b128 v[164:167], v242 offset:62464
	v_exp_f32_e32 v168, v168
	v_exp_f32_e32 v169, v169
	v_add_f32_e32 v15, v168, v15
	v_cvt_pk_bf16_f32 v184, v168, v169
	v_add_f32_e32 v15, v169, v15
	s_waitcnt lgkmcnt(2)
	v_mfma_f32_32x32x16_bf16 v[80:95], v[234:237], v[180:183], v[80:95]
	ds_read_b128 v[176:179], v243 offset:13920
	v_exp_f32_e32 v168, v170
	v_exp_f32_e32 v169, v171
	v_add_f32_e32 v15, v168, v15
	v_cvt_pk_bf16_f32 v185, v168, v169
	v_add_f32_e32 v15, v169, v15
	s_waitcnt lgkmcnt(1)
	v_mfma_f32_32x32x16_bf16 v[128:143], v[160:163], v[164:167], v[128:143]
	ds_read_b64_tr_b16 v[168:169], v244 offset:38912
	ds_read_b64_tr_b16 v[170:171], v244 offset:41472
	v_exp_f32_e32 v160, v172
	v_exp_f32_e32 v161, v173
	v_add_f32_e32 v15, v160, v15
	v_cvt_pk_bf16_f32 v186, v160, v161
	v_add_f32_e32 v15, v161, v15
	s_waitcnt lgkmcnt(2)
	v_mfma_f32_32x32x16_bf16 v[80:95], v[176:179], v[164:167], v[80:95]
	ds_read_b64_tr_b16 v[160:161], v244 offset:38976
	ds_read_b64_tr_b16 v[162:163], v244 offset:41536
	v_exp_f32_e32 v172, v174
	v_exp_f32_e32 v173, v175
	v_add_f32_e32 v15, v172, v15
	v_cvt_pk_bf16_f32 v187, v172, v173
	v_add_f32_e32 v15, v173, v15
	s_waitcnt lgkmcnt(2)
	v_mfma_f32_32x32x16_bf16 v[64:79], v[168:171], v[10:13], v[64:79]
	ds_read_b64_tr_b16 v[164:165], v244 offset:39040
	ds_read_b64_tr_b16 v[166:167], v244 offset:41600
	v_exp_f32_e32 v144, v144
	v_max3_f32 v172, v128, s33, v80
	v_add_f32_e32 v15, v144, v15
	s_waitcnt lgkmcnt(2)
	v_mfma_f32_32x32x16_bf16 v[48:63], v[160:163], v[10:13], v[48:63]
	ds_read_b64_tr_b16 v[168:169], v244 offset:39104
	v_exp_f32_e32 v145, v145
	ds_read_b64_tr_b16 v[170:171], v244 offset:41664
	v_cvt_pk_bf16_f32 v176, v144, v145
	v_max3_f32 v144, v172, v129, v81
	v_add_f32_e32 v15, v145, v15
	s_waitcnt lgkmcnt(2)
	v_mfma_f32_32x32x16_bf16 v[32:47], v[164:167], v[10:13], v[32:47]
	ds_read_b64_tr_b16 v[160:161], v244 offset:44032
	ds_read_b64_tr_b16 v[162:163], v244 offset:46592
	v_exp_f32_e32 v145, v146
	v_max3_f32 v144, v144, v130, v82
	v_add_f32_e32 v15, v145, v15
	s_waitcnt lgkmcnt(2)
	v_mfma_f32_32x32x16_bf16 v[16:31], v[168:171], v[10:13], v[16:31]
	ds_read_b64_tr_b16 v[164:165], v244 offset:44096
	ds_read_b64_tr_b16 v[166:167], v244 offset:46656
	v_exp_f32_e32 v10, v147
	v_max3_f32 v144, v144, v131, v83
	v_cvt_pk_bf16_f32 v177, v145, v10
	v_add_f32_e32 v15, v10, v15
	s_waitcnt lgkmcnt(2)
	v_mfma_f32_32x32x16_bf16 v[64:79], v[160:163], v[6:9], v[64:79]
	ds_read_b64_tr_b16 v[10:11], v244 offset:44160
	ds_read_b64_tr_b16 v[12:13], v244 offset:46720
	v_exp_f32_e32 v148, v148
	v_max3_f32 v160, v144, v132, v84
	v_add_f32_e32 v15, v148, v15
	s_waitcnt lgkmcnt(2)
	v_mfma_f32_32x32x16_bf16 v[48:63], v[164:167], v[6:9], v[48:63]
	ds_read_b64_tr_b16 v[144:145], v244 offset:44224
	v_exp_f32_e32 v149, v149
	ds_read_b64_tr_b16 v[146:147], v244 offset:46784
	v_cvt_pk_bf16_f32 v178, v148, v149
	v_max3_f32 v148, v160, v133, v85
	v_add_f32_e32 v15, v149, v15
	s_waitcnt lgkmcnt(2)
	v_mfma_f32_32x32x16_bf16 v[32:47], v[10:13], v[6:9], v[32:47]
	ds_read_b64_tr_b16 v[160:161], v244 offset:49152
	ds_read_b64_tr_b16 v[162:163], v244 offset:51712
	v_exp_f32_e32 v149, v150
	v_max3_f32 v148, v148, v134, v86
	v_add_f32_e32 v15, v149, v15
	s_waitcnt lgkmcnt(2)
	v_mfma_f32_32x32x16_bf16 v[16:31], v[144:147], v[6:9], v[16:31]
	ds_read_b64_tr_b16 v[10:11], v244 offset:49216
	ds_read_b64_tr_b16 v[12:13], v244 offset:51776
	v_exp_f32_e32 v6, v151
	v_max3_f32 v144, v148, v135, v87
	v_cvt_pk_bf16_f32 v179, v149, v6
	v_add_f32_e32 v15, v6, v15
	s_waitcnt lgkmcnt(2)
	v_mfma_f32_32x32x16_bf16 v[64:79], v[160:163], v[2:5], v[64:79]
	ds_read_b64_tr_b16 v[6:7], v244 offset:49280
	ds_read_b64_tr_b16 v[8:9], v244 offset:51840
	v_exp_f32_e32 v148, v152
	v_max3_f32 v149, v144, v136, v88
	v_add_f32_e32 v15, v148, v15
	s_waitcnt lgkmcnt(2)
	v_mfma_f32_32x32x16_bf16 v[48:63], v[10:13], v[2:5], v[48:63]
	ds_read_b64_tr_b16 v[144:145], v244 offset:49344
	v_exp_f32_e32 v10, v153
	ds_read_b64_tr_b16 v[146:147], v244 offset:51904
	v_cvt_pk_bf16_f32 v180, v148, v10
	v_max3_f32 v148, v149, v137, v89
	v_add_f32_e32 v15, v10, v15
	s_waitcnt lgkmcnt(2)
	v_mfma_f32_32x32x16_bf16 v[32:47], v[6:9], v[2:5], v[32:47]
	ds_read_b64_tr_b16 v[10:11], v244 offset:54272
	ds_read_b64_tr_b16 v[12:13], v244 offset:56832
	v_exp_f32_e32 v149, v154
	v_max3_f32 v148, v148, v138, v90
	v_add_f32_e32 v15, v149, v15
	s_waitcnt lgkmcnt(2)
	v_mfma_f32_32x32x16_bf16 v[16:31], v[144:147], v[2:5], v[16:31]
	ds_read_b64_tr_b16 v[6:7], v244 offset:54336
	ds_read_b64_tr_b16 v[8:9], v244 offset:56896
	v_exp_f32_e32 v2, v155
	v_max3_f32 v144, v148, v139, v91
	v_cvt_pk_bf16_f32 v181, v149, v2
	v_add_f32_e32 v15, v2, v15
	s_waitcnt lgkmcnt(2)
	v_mfma_f32_32x32x16_bf16 v[64:79], v[10:13], v[192:195], v[64:79]
	ds_read_b64_tr_b16 v[2:3], v244 offset:54400
	ds_read_b64_tr_b16 v[4:5], v244 offset:56960
	v_exp_f32_e32 v145, v156
	v_max3_f32 v144, v144, v140, v92
	v_add_f32_e32 v15, v145, v15
	s_waitcnt lgkmcnt(2)
	v_mfma_f32_32x32x16_bf16 v[48:63], v[6:9], v[192:195], v[48:63]
	ds_read_b64_tr_b16 v[10:11], v244 offset:54464
	v_exp_f32_e32 v6, v157
	ds_read_b64_tr_b16 v[12:13], v244 offset:57024
	v_add_f32_e32 v7, v6, v15
	v_cvt_pk_bf16_f32 v182, v145, v6
	v_max3_f32 v6, v144, v141, v93
	s_waitcnt lgkmcnt(2)
	v_mfma_f32_32x32x16_bf16 v[32:47], v[2:5], v[192:195], v[32:47]
	v_exp_f32_e32 v3, v158
	v_max3_f32 v4, v6, v142, v94
	v_add_f32_e32 v2, v3, v7
	s_waitcnt lgkmcnt(0)
	v_mfma_f32_32x32x16_bf16 v[16:31], v[10:13], v[192:195], v[16:31]
	v_exp_f32_e32 v5, v159
	s_nop 0
	v_add_f32_e32 v2, v5, v2
	v_cvt_pk_bf16_f32 v183, v3, v5
	v_max3_f32 v3, v4, v143, v95
	v_mov_b32_e32 v4, v2
	v_cmp_gt_f32_e32 vcc, 1.0, v0
	s_nop 0
	v_permlane32_swap_b32_e32 v2, v4
	s_cbranch_vccz .LBB0_589
	v_pk_mul_f32 v[78:79], v[0:1], v[78:79] op_sel_hi:[0,1]
	v_pk_mul_f32 v[76:77], v[0:1], v[76:77] op_sel_hi:[0,1]
	v_pk_mul_f32 v[74:75], v[0:1], v[74:75] op_sel_hi:[0,1]
	v_pk_mul_f32 v[72:73], v[0:1], v[72:73] op_sel_hi:[0,1]
	v_pk_mul_f32 v[70:71], v[0:1], v[70:71] op_sel_hi:[0,1]
	v_pk_mul_f32 v[68:69], v[0:1], v[68:69] op_sel_hi:[0,1]
	v_pk_mul_f32 v[66:67], v[0:1], v[66:67] op_sel_hi:[0,1]
	v_pk_mul_f32 v[64:65], v[0:1], v[64:65] op_sel_hi:[0,1]
	v_pk_mul_f32 v[62:63], v[0:1], v[62:63] op_sel_hi:[0,1]
	v_pk_mul_f32 v[60:61], v[0:1], v[60:61] op_sel_hi:[0,1]
	v_pk_mul_f32 v[58:59], v[0:1], v[58:59] op_sel_hi:[0,1]
	v_pk_mul_f32 v[56:57], v[0:1], v[56:57] op_sel_hi:[0,1]
	v_pk_mul_f32 v[54:55], v[0:1], v[54:55] op_sel_hi:[0,1]
	v_pk_mul_f32 v[52:53], v[0:1], v[52:53] op_sel_hi:[0,1]
	v_pk_mul_f32 v[50:51], v[0:1], v[50:51] op_sel_hi:[0,1]
	v_pk_mul_f32 v[48:49], v[0:1], v[48:49] op_sel_hi:[0,1]
	v_pk_mul_f32 v[46:47], v[0:1], v[46:47] op_sel_hi:[0,1]
	v_pk_mul_f32 v[44:45], v[0:1], v[44:45] op_sel_hi:[0,1]
	v_pk_mul_f32 v[42:43], v[0:1], v[42:43] op_sel_hi:[0,1]
	v_pk_mul_f32 v[40:41], v[0:1], v[40:41] op_sel_hi:[0,1]
	v_pk_mul_f32 v[38:39], v[0:1], v[38:39] op_sel_hi:[0,1]
	v_pk_mul_f32 v[36:37], v[0:1], v[36:37] op_sel_hi:[0,1]
	v_pk_mul_f32 v[34:35], v[0:1], v[34:35] op_sel_hi:[0,1]
	v_pk_mul_f32 v[32:33], v[0:1], v[32:33] op_sel_hi:[0,1]
	v_pk_mul_f32 v[30:31], v[0:1], v[30:31] op_sel_hi:[0,1]
	v_pk_mul_f32 v[28:29], v[0:1], v[28:29] op_sel_hi:[0,1]
	v_pk_mul_f32 v[26:27], v[0:1], v[26:27] op_sel_hi:[0,1]
	v_pk_mul_f32 v[24:25], v[0:1], v[24:25] op_sel_hi:[0,1]
	v_pk_mul_f32 v[22:23], v[0:1], v[22:23] op_sel_hi:[0,1]
	v_pk_mul_f32 v[20:21], v[0:1], v[20:21] op_sel_hi:[0,1]
	v_pk_mul_f32 v[18:19], v[0:1], v[18:19] op_sel_hi:[0,1]
	v_pk_mul_f32 v[16:17], v[0:1], v[16:17] op_sel_hi:[0,1]
.LBB0_589:
	v_add_f32_e32 v0, v2, v4
	v_add_f32_e32 v222, v14, v0
	v_mov_b32_e32 v0, v3
	s_cmp_ge_u32 s13, s16
	v_mov_b32_e32 v220, 1.0
	v_permlane32_swap_b32_e32 v3, v0
	s_cbranch_scc1 .LBB0_593
	v_max_f32_e32 v2, v3, v3
	v_max_f32_e32 v0, v0, v0
	v_max_f32_e32 v0, v2, v0
	v_cmp_lt_f32_e32 vcc, s28, v0
	s_cbranch_vccz .LBB0_592
	v_max_f32_e32 v0, v0, v0
	v_max_f32_e32 v0, 0, v0
	v_exp_f32_e64 v220, -v0
	v_add_f32_e32 v221, v221, v0
	v_xor_b32_e32 v112, 0x80000000, v221
	v_sub_f32_e32 v143, v143, v0
	v_sub_f32_e32 v142, v142, v0
	v_sub_f32_e32 v141, v141, v0
	v_sub_f32_e32 v140, v140, v0
	v_sub_f32_e32 v139, v139, v0
	v_sub_f32_e32 v138, v138, v0
	v_sub_f32_e32 v137, v137, v0
	v_sub_f32_e32 v136, v136, v0
	v_sub_f32_e32 v135, v135, v0
	v_sub_f32_e32 v134, v134, v0
	v_sub_f32_e32 v133, v133, v0
	v_sub_f32_e32 v132, v132, v0
	v_sub_f32_e32 v131, v131, v0
	v_sub_f32_e32 v130, v130, v0
	v_sub_f32_e32 v129, v129, v0
	v_sub_f32_e32 v128, v128, v0
	v_sub_f32_e32 v95, v95, v0
	v_sub_f32_e32 v94, v94, v0
	v_sub_f32_e32 v93, v93, v0
	v_sub_f32_e32 v92, v92, v0
	v_sub_f32_e32 v91, v91, v0
	v_sub_f32_e32 v90, v90, v0
	v_sub_f32_e32 v89, v89, v0
	v_sub_f32_e32 v88, v88, v0
	v_sub_f32_e32 v87, v87, v0
	v_sub_f32_e32 v86, v86, v0
	v_sub_f32_e32 v85, v85, v0
	v_sub_f32_e32 v84, v84, v0
	v_sub_f32_e32 v83, v83, v0
	v_sub_f32_e32 v82, v82, v0
	v_sub_f32_e32 v81, v81, v0
	v_sub_f32_e32 v80, v80, v0
	v_mul_f32_e32 v222, v222, v220
	v_mov_b32_e32 v113, v112
	v_mov_b32_e32 v114, v112
	v_mov_b32_e32 v115, v112
	v_mov_b32_e32 v116, v112
	v_mov_b32_e32 v117, v112
	v_mov_b32_e32 v118, v112
	v_mov_b32_e32 v119, v112
	v_mov_b32_e32 v120, v112
	v_mov_b32_e32 v121, v112
	v_mov_b32_e32 v122, v112
	v_mov_b32_e32 v123, v112
	v_mov_b32_e32 v124, v112
	v_mov_b32_e32 v125, v112
	v_mov_b32_e32 v126, v112
	v_mov_b32_e32 v127, v112
	v_mov_b32_e32 v111, v112
	v_mov_b32_e32 v110, v112
	v_mov_b32_e32 v109, v112
	v_mov_b32_e32 v108, v112
	v_mov_b32_e32 v107, v112
	v_mov_b32_e32 v106, v112
	v_mov_b32_e32 v105, v112
	v_mov_b32_e32 v104, v112
	v_mov_b32_e32 v103, v112
	v_mov_b32_e32 v102, v112
	v_mov_b32_e32 v101, v112
	v_mov_b32_e32 v100, v112
	v_mov_b32_e32 v99, v112
	v_mov_b32_e32 v98, v112
	v_mov_b32_e32 v97, v112
	v_mov_b32_e32 v96, v112
	s_branch .LBB0_593
